# v18 plus code placement: the 8 GEMM K-loop heads pinned to 0 mod 8 bytes with .p2align 3
# baseline (speedup 1.0000x reference)
.LBB0_153:
	s_ashr_i32 s11, s10, 31
	v_cmp_lt_i64_e32 vcc, s[12:13], v[140:141]
	s_lshl_b64 s[12:13], s[10:11], 20
	v_readlane_b32 s14, v247, 9
	v_readlane_b32 s15, v247, 10
	s_add_u32 s12, s14, s12
	s_addc_u32 s13, s15, s13
	s_and_b64 s[14:15], vcc, exec
	s_cselect_b32 s11, s13, s17
	s_cselect_b32 s36, s12, s16
	s_ashr_i32 s9, s8, 31
	s_lshl_b64 s[14:15], s[8:9], 20
	s_add_u32 s14, s58, s14
	s_addc_u32 s15, s59, s15
	s_and_b64 s[20:21], vcc, exec
	s_cselect_b32 s9, s15, s19
	s_cselect_b32 s37, s14, s18
	s_add_u32 s16, s16, 0x80080
	s_addc_u32 s17, s17, 0
	s_add_u32 s38, s18, 0x100
	v_mov_b32_e32 v0, 0
	s_addc_u32 s39, s19, 0
	s_mov_b32 s40, -2
	v_mov_b32_e32 v1, v0
	v_mov_b32_e32 v2, v0
	v_mov_b32_e32 v3, v0
	v_mov_b32_e32 v4, v0
	v_mov_b32_e32 v5, v0
	v_mov_b32_e32 v6, v0
	v_mov_b32_e32 v7, v0
	v_mov_b32_e32 v8, v0
	v_mov_b32_e32 v9, v0
	v_mov_b32_e32 v10, v0
	v_mov_b32_e32 v11, v0
	v_mov_b32_e32 v12, v0
	v_mov_b32_e32 v13, v0
	v_mov_b32_e32 v14, v0
	v_mov_b32_e32 v15, v0
	v_mov_b32_e32 v24, v0
	v_mov_b32_e32 v25, v0
	v_mov_b32_e32 v26, v0
	v_mov_b32_e32 v27, v0
	v_mov_b32_e32 v28, v0
	v_mov_b32_e32 v29, v0
	v_mov_b32_e32 v30, v0
	v_mov_b32_e32 v31, v0
	v_mov_b32_e32 v40, v0
	v_mov_b32_e32 v41, v0
	v_mov_b32_e32 v42, v0
	v_mov_b32_e32 v43, v0
	v_mov_b32_e32 v44, v0
	v_mov_b32_e32 v45, v0
	v_mov_b32_e32 v46, v0
	v_mov_b32_e32 v47, v0
	v_mov_b32_e32 v16, v0
	v_mov_b32_e32 v17, v0
	v_mov_b32_e32 v18, v0
	v_mov_b32_e32 v19, v0
	v_mov_b32_e32 v20, v0
	v_mov_b32_e32 v21, v0
	v_mov_b32_e32 v22, v0
	v_mov_b32_e32 v23, v0
	v_mov_b32_e32 v32, v0
	v_mov_b32_e32 v33, v0
	v_mov_b32_e32 v34, v0
	v_mov_b32_e32 v35, v0
	v_mov_b32_e32 v36, v0
	v_mov_b32_e32 v37, v0
	v_mov_b32_e32 v38, v0
	v_mov_b32_e32 v39, v0
	v_mov_b32_e32 v48, v0
	v_mov_b32_e32 v49, v0
	v_mov_b32_e32 v50, v0
	v_mov_b32_e32 v51, v0
	v_mov_b32_e32 v52, v0
	v_mov_b32_e32 v53, v0
	v_mov_b32_e32 v54, v0
	v_mov_b32_e32 v55, v0
	v_mov_b32_e32 v56, v0
	v_mov_b32_e32 v57, v0
	v_mov_b32_e32 v58, v0
	v_mov_b32_e32 v59, v0
	v_mov_b32_e32 v60, v0
	v_mov_b32_e32 v61, v0
	v_mov_b32_e32 v62, v0
	v_mov_b32_e32 v63, v0
	v_mov_b32_e32 v64, v0
	v_mov_b32_e32 v65, v0
	v_mov_b32_e32 v66, v0
	v_mov_b32_e32 v67, v0
	v_mov_b32_e32 v68, v0
	v_mov_b32_e32 v69, v0
	v_mov_b32_e32 v70, v0
	v_mov_b32_e32 v71, v0
	v_mov_b32_e32 v72, v0
	v_mov_b32_e32 v73, v0
	v_mov_b32_e32 v74, v0
	v_mov_b32_e32 v75, v0
	v_mov_b32_e32 v76, v0
	v_mov_b32_e32 v77, v0
	v_mov_b32_e32 v78, v0
	v_mov_b32_e32 v79, v0
	v_mov_b32_e32 v88, v0
	v_mov_b32_e32 v89, v0
	v_mov_b32_e32 v90, v0
	v_mov_b32_e32 v91, v0
	v_mov_b32_e32 v92, v0
	v_mov_b32_e32 v93, v0
	v_mov_b32_e32 v94, v0
	v_mov_b32_e32 v95, v0
	v_mov_b32_e32 v104, v0
	v_mov_b32_e32 v105, v0
	v_mov_b32_e32 v106, v0
	v_mov_b32_e32 v107, v0
	v_mov_b32_e32 v108, v0
	v_mov_b32_e32 v109, v0
	v_mov_b32_e32 v110, v0
	v_mov_b32_e32 v111, v0
	v_mov_b32_e32 v80, v0
	v_mov_b32_e32 v81, v0
	v_mov_b32_e32 v82, v0
	v_mov_b32_e32 v83, v0
	v_mov_b32_e32 v84, v0
	v_mov_b32_e32 v85, v0
	v_mov_b32_e32 v86, v0
	v_mov_b32_e32 v87, v0
	v_mov_b32_e32 v96, v0
	v_mov_b32_e32 v97, v0
	v_mov_b32_e32 v98, v0
	v_mov_b32_e32 v99, v0
	v_mov_b32_e32 v100, v0
	v_mov_b32_e32 v101, v0
	v_mov_b32_e32 v102, v0
	v_mov_b32_e32 v103, v0
	v_mov_b32_e32 v112, v0
	v_mov_b32_e32 v113, v0
	v_mov_b32_e32 v114, v0
	v_mov_b32_e32 v115, v0
	v_mov_b32_e32 v116, v0
	v_mov_b32_e32 v117, v0
	v_mov_b32_e32 v118, v0
	v_mov_b32_e32 v119, v0
	v_mov_b32_e32 v120, v0
	v_mov_b32_e32 v121, v0
	v_mov_b32_e32 v122, v0
	v_mov_b32_e32 v123, v0
	v_mov_b32_e32 v124, v0
	v_mov_b32_e32 v125, v0
	v_mov_b32_e32 v126, v0
	v_mov_b32_e32 v127, v0
	.p2align 3

.LBB0_366:
	s_ashr_i32 s9, s8, 31
	s_lshl_b64 s[20:21], s[8:9], 20
	s_add_u32 s20, s14, s20
	s_addc_u32 s21, s15, s21
	s_ashr_i32 s7, s6, 31
	s_lshl_b64 s[22:23], s[6:7], 20
	s_add_u32 s22, s4, s22
	s_addc_u32 s23, s5, s23
	s_cmp_lt_i32 s46, 1
	s_cbranch_scc1 .LBB0_362
	s_and_b64 s[28:29], s[28:29], exec
	s_cselect_b32 s7, s21, s25
	s_cselect_b32 s9, s20, s24
	s_cselect_b32 s47, s23, s27
	s_cselect_b32 s48, s22, s26
	s_add_i32 s49, s46, -2
	s_add_u32 s24, s24, 0x80080
	s_addc_u32 s25, s25, 0
	s_add_u32 s50, s26, 0x100
	v_mov_b32_e32 v0, 0
	s_addc_u32 s51, s27, 0
	s_mov_b32 s26, 0
	v_mov_b32_e32 v1, v0
	v_mov_b32_e32 v2, v0
	v_mov_b32_e32 v3, v0
	v_mov_b32_e32 v4, v0
	v_mov_b32_e32 v5, v0
	v_mov_b32_e32 v6, v0
	v_mov_b32_e32 v7, v0
	v_mov_b32_e32 v16, v0
	v_mov_b32_e32 v17, v0
	v_mov_b32_e32 v18, v0
	v_mov_b32_e32 v19, v0
	v_mov_b32_e32 v20, v0
	v_mov_b32_e32 v21, v0
	v_mov_b32_e32 v22, v0
	v_mov_b32_e32 v23, v0
	v_mov_b32_e32 v32, v0
	v_mov_b32_e32 v33, v0
	v_mov_b32_e32 v34, v0
	v_mov_b32_e32 v35, v0
	v_mov_b32_e32 v36, v0
	v_mov_b32_e32 v37, v0
	v_mov_b32_e32 v38, v0
	v_mov_b32_e32 v39, v0
	v_mov_b32_e32 v48, v0
	v_mov_b32_e32 v49, v0
	v_mov_b32_e32 v50, v0
	v_mov_b32_e32 v51, v0
	v_mov_b32_e32 v52, v0
	v_mov_b32_e32 v53, v0
	v_mov_b32_e32 v54, v0
	v_mov_b32_e32 v55, v0
	v_mov_b32_e32 v8, v0
	v_mov_b32_e32 v9, v0
	v_mov_b32_e32 v10, v0
	v_mov_b32_e32 v11, v0
	v_mov_b32_e32 v12, v0
	v_mov_b32_e32 v13, v0
	v_mov_b32_e32 v14, v0
	v_mov_b32_e32 v15, v0
	v_mov_b32_e32 v24, v0
	v_mov_b32_e32 v25, v0
	v_mov_b32_e32 v26, v0
	v_mov_b32_e32 v27, v0
	v_mov_b32_e32 v28, v0
	v_mov_b32_e32 v29, v0
	v_mov_b32_e32 v30, v0
	v_mov_b32_e32 v31, v0
	v_mov_b32_e32 v40, v0
	v_mov_b32_e32 v41, v0
	v_mov_b32_e32 v42, v0
	v_mov_b32_e32 v43, v0
	v_mov_b32_e32 v44, v0
	v_mov_b32_e32 v45, v0
	v_mov_b32_e32 v46, v0
	v_mov_b32_e32 v47, v0
	v_mov_b32_e32 v56, v0
	v_mov_b32_e32 v57, v0
	v_mov_b32_e32 v58, v0
	v_mov_b32_e32 v59, v0
	v_mov_b32_e32 v60, v0
	v_mov_b32_e32 v61, v0
	v_mov_b32_e32 v62, v0
	v_mov_b32_e32 v63, v0
	v_mov_b32_e32 v64, v0
	v_mov_b32_e32 v65, v0
	v_mov_b32_e32 v66, v0
	v_mov_b32_e32 v67, v0
	v_mov_b32_e32 v68, v0
	v_mov_b32_e32 v69, v0
	v_mov_b32_e32 v70, v0
	v_mov_b32_e32 v71, v0
	v_mov_b32_e32 v80, v0
	v_mov_b32_e32 v81, v0
	v_mov_b32_e32 v82, v0
	v_mov_b32_e32 v83, v0
	v_mov_b32_e32 v84, v0
	v_mov_b32_e32 v85, v0
	v_mov_b32_e32 v86, v0
	v_mov_b32_e32 v87, v0
	v_mov_b32_e32 v96, v0
	v_mov_b32_e32 v97, v0
	v_mov_b32_e32 v98, v0
	v_mov_b32_e32 v99, v0
	v_mov_b32_e32 v100, v0
	v_mov_b32_e32 v101, v0
	v_mov_b32_e32 v102, v0
	v_mov_b32_e32 v103, v0
	v_mov_b32_e32 v112, v0
	v_mov_b32_e32 v113, v0
	v_mov_b32_e32 v114, v0
	v_mov_b32_e32 v115, v0
	v_mov_b32_e32 v116, v0
	v_mov_b32_e32 v117, v0
	v_mov_b32_e32 v118, v0
	v_mov_b32_e32 v119, v0
	v_mov_b32_e32 v72, v0
	v_mov_b32_e32 v73, v0
	v_mov_b32_e32 v74, v0
	v_mov_b32_e32 v75, v0
	v_mov_b32_e32 v76, v0
	v_mov_b32_e32 v77, v0
	v_mov_b32_e32 v78, v0
	v_mov_b32_e32 v79, v0
	v_mov_b32_e32 v88, v0
	v_mov_b32_e32 v89, v0
	v_mov_b32_e32 v90, v0
	v_mov_b32_e32 v91, v0
	v_mov_b32_e32 v92, v0
	v_mov_b32_e32 v93, v0
	v_mov_b32_e32 v94, v0
	v_mov_b32_e32 v95, v0
	v_mov_b32_e32 v104, v0
	v_mov_b32_e32 v105, v0
	v_mov_b32_e32 v106, v0
	v_mov_b32_e32 v107, v0
	v_mov_b32_e32 v108, v0
	v_mov_b32_e32 v109, v0
	v_mov_b32_e32 v110, v0
	v_mov_b32_e32 v111, v0
	v_mov_b32_e32 v120, v0
	v_mov_b32_e32 v121, v0
	v_mov_b32_e32 v122, v0
	v_mov_b32_e32 v123, v0
	v_mov_b32_e32 v124, v0
	v_mov_b32_e32 v125, v0
	v_mov_b32_e32 v126, v0
	v_mov_b32_e32 v127, v0
	.p2align 3

.LBB0_530:
	s_ashr_i32 s15, s14, 31
	v_cmp_lt_i64_e32 vcc, s[16:17], v[140:141]
	s_lshl_b64 s[16:17], s[14:15], 20
	v_readlane_b32 s18, v247, 9
	v_readlane_b32 s19, v247, 10
	s_add_u32 s16, s18, s16
	s_addc_u32 s17, s19, s17
	s_and_b64 s[18:19], vcc, exec
	s_cselect_b32 s15, s17, s23
	s_cselect_b32 s41, s16, s22
	s_ashr_i32 s9, s8, 31
	s_lshl_b64 s[18:19], s[8:9], 20
	s_add_u32 s18, s0, s18
	s_addc_u32 s19, s1, s19
	s_and_b64 s[26:27], vcc, exec
	s_cselect_b32 s9, s19, s25
	s_cselect_b32 s42, s18, s24
	s_add_u32 s22, s22, 0x80080
	s_addc_u32 s23, s23, 0
	s_add_u32 s43, s24, 0x100
	v_mov_b32_e32 v0, 0
	s_addc_u32 s44, s25, 0
	s_mov_b32 s45, -2
	v_mov_b32_e32 v1, v0
	v_mov_b32_e32 v2, v0
	v_mov_b32_e32 v3, v0
	v_mov_b32_e32 v4, v0
	v_mov_b32_e32 v5, v0
	v_mov_b32_e32 v6, v0
	v_mov_b32_e32 v7, v0
	v_mov_b32_e32 v16, v0
	v_mov_b32_e32 v17, v0
	v_mov_b32_e32 v18, v0
	v_mov_b32_e32 v19, v0
	v_mov_b32_e32 v20, v0
	v_mov_b32_e32 v21, v0
	v_mov_b32_e32 v22, v0
	v_mov_b32_e32 v23, v0
	v_mov_b32_e32 v32, v0
	v_mov_b32_e32 v33, v0
	v_mov_b32_e32 v34, v0
	v_mov_b32_e32 v35, v0
	v_mov_b32_e32 v36, v0
	v_mov_b32_e32 v37, v0
	v_mov_b32_e32 v38, v0
	v_mov_b32_e32 v39, v0
	v_mov_b32_e32 v48, v0
	v_mov_b32_e32 v49, v0
	v_mov_b32_e32 v50, v0
	v_mov_b32_e32 v51, v0
	v_mov_b32_e32 v52, v0
	v_mov_b32_e32 v53, v0
	v_mov_b32_e32 v54, v0
	v_mov_b32_e32 v55, v0
	v_mov_b32_e32 v8, v0
	v_mov_b32_e32 v9, v0
	v_mov_b32_e32 v10, v0
	v_mov_b32_e32 v11, v0
	v_mov_b32_e32 v12, v0
	v_mov_b32_e32 v13, v0
	v_mov_b32_e32 v14, v0
	v_mov_b32_e32 v15, v0
	v_mov_b32_e32 v24, v0
	v_mov_b32_e32 v25, v0
	v_mov_b32_e32 v26, v0
	v_mov_b32_e32 v27, v0
	v_mov_b32_e32 v28, v0
	v_mov_b32_e32 v29, v0
	v_mov_b32_e32 v30, v0
	v_mov_b32_e32 v31, v0
	v_mov_b32_e32 v40, v0
	v_mov_b32_e32 v41, v0
	v_mov_b32_e32 v42, v0
	v_mov_b32_e32 v43, v0
	v_mov_b32_e32 v44, v0
	v_mov_b32_e32 v45, v0
	v_mov_b32_e32 v46, v0
	v_mov_b32_e32 v47, v0
	v_mov_b32_e32 v56, v0
	v_mov_b32_e32 v57, v0
	v_mov_b32_e32 v58, v0
	v_mov_b32_e32 v59, v0
	v_mov_b32_e32 v60, v0
	v_mov_b32_e32 v61, v0
	v_mov_b32_e32 v62, v0
	v_mov_b32_e32 v63, v0
	v_mov_b32_e32 v64, v0
	v_mov_b32_e32 v65, v0
	v_mov_b32_e32 v66, v0
	v_mov_b32_e32 v67, v0
	v_mov_b32_e32 v68, v0
	v_mov_b32_e32 v69, v0
	v_mov_b32_e32 v70, v0
	v_mov_b32_e32 v71, v0
	v_mov_b32_e32 v80, v0
	v_mov_b32_e32 v81, v0
	v_mov_b32_e32 v82, v0
	v_mov_b32_e32 v83, v0
	v_mov_b32_e32 v84, v0
	v_mov_b32_e32 v85, v0
	v_mov_b32_e32 v86, v0
	v_mov_b32_e32 v87, v0
	v_mov_b32_e32 v96, v0
	v_mov_b32_e32 v97, v0
	v_mov_b32_e32 v98, v0
	v_mov_b32_e32 v99, v0
	v_mov_b32_e32 v100, v0
	v_mov_b32_e32 v101, v0
	v_mov_b32_e32 v102, v0
	v_mov_b32_e32 v103, v0
	v_mov_b32_e32 v112, v0
	v_mov_b32_e32 v113, v0
	v_mov_b32_e32 v114, v0
	v_mov_b32_e32 v115, v0
	v_mov_b32_e32 v116, v0
	v_mov_b32_e32 v117, v0
	v_mov_b32_e32 v118, v0
	v_mov_b32_e32 v119, v0
	v_mov_b32_e32 v72, v0
	v_mov_b32_e32 v73, v0
	v_mov_b32_e32 v74, v0
	v_mov_b32_e32 v75, v0
	v_mov_b32_e32 v76, v0
	v_mov_b32_e32 v77, v0
	v_mov_b32_e32 v78, v0
	v_mov_b32_e32 v79, v0
	v_mov_b32_e32 v88, v0
	v_mov_b32_e32 v89, v0
	v_mov_b32_e32 v90, v0
	v_mov_b32_e32 v91, v0
	v_mov_b32_e32 v92, v0
	v_mov_b32_e32 v93, v0
	v_mov_b32_e32 v94, v0
	v_mov_b32_e32 v95, v0
	v_mov_b32_e32 v104, v0
	v_mov_b32_e32 v105, v0
	v_mov_b32_e32 v106, v0
	v_mov_b32_e32 v107, v0
	v_mov_b32_e32 v108, v0
	v_mov_b32_e32 v109, v0
	v_mov_b32_e32 v110, v0
	v_mov_b32_e32 v111, v0
	v_mov_b32_e32 v120, v0
	v_mov_b32_e32 v121, v0
	v_mov_b32_e32 v122, v0
	v_mov_b32_e32 v123, v0
	v_mov_b32_e32 v124, v0
	v_mov_b32_e32 v125, v0
	v_mov_b32_e32 v126, v0
	v_mov_b32_e32 v127, v0
	.p2align 3

.LBB0_642:
	s_ashr_i32 s5, s4, 31
	s_lshl_b64 s[8:9], s[4:5], 22
	v_readlane_b32 s12, v248, 63
	v_readlane_b32 s13, v247, 0
	s_add_u32 s8, s12, s8
	s_addc_u32 s9, s13, s9
	s_ashr_i32 s3, s2, 31
	s_lshl_b64 s[12:13], s[2:3], 22
	s_add_u32 s12, s23, s12
	s_addc_u32 s13, s24, s13
	s_cmp_lt_i32 s40, 1
	s_cbranch_scc1 .LBB0_638
	s_and_b64 s[20:21], s[20:21], exec
	s_cselect_b32 s3, s9, s17
	s_cselect_b32 s5, s8, s16
	s_cselect_b32 s41, s13, s19
	s_cselect_b32 s42, s12, s18
	s_add_i32 s43, s40, -2
	s_add_u32 s16, s16, 0x200080
	s_addc_u32 s17, s17, 0
	s_add_u32 s44, s18, 0x100
	v_mov_b32_e32 v0, 0
	s_addc_u32 s45, s19, 0
	s_mov_b32 s18, 0
	v_mov_b32_e32 v1, v0
	v_mov_b32_e32 v2, v0
	v_mov_b32_e32 v3, v0
	v_mov_b32_e32 v4, v0
	v_mov_b32_e32 v5, v0
	v_mov_b32_e32 v6, v0
	v_mov_b32_e32 v7, v0
	v_mov_b32_e32 v16, v0
	v_mov_b32_e32 v17, v0
	v_mov_b32_e32 v18, v0
	v_mov_b32_e32 v19, v0
	v_mov_b32_e32 v20, v0
	v_mov_b32_e32 v21, v0
	v_mov_b32_e32 v22, v0
	v_mov_b32_e32 v23, v0
	v_mov_b32_e32 v32, v0
	v_mov_b32_e32 v33, v0
	v_mov_b32_e32 v34, v0
	v_mov_b32_e32 v35, v0
	v_mov_b32_e32 v36, v0
	v_mov_b32_e32 v37, v0
	v_mov_b32_e32 v38, v0
	v_mov_b32_e32 v39, v0
	v_mov_b32_e32 v48, v0
	v_mov_b32_e32 v49, v0
	v_mov_b32_e32 v50, v0
	v_mov_b32_e32 v51, v0
	v_mov_b32_e32 v52, v0
	v_mov_b32_e32 v53, v0
	v_mov_b32_e32 v54, v0
	v_mov_b32_e32 v55, v0
	v_mov_b32_e32 v8, v0
	v_mov_b32_e32 v9, v0
	v_mov_b32_e32 v10, v0
	v_mov_b32_e32 v11, v0
	v_mov_b32_e32 v12, v0
	v_mov_b32_e32 v13, v0
	v_mov_b32_e32 v14, v0
	v_mov_b32_e32 v15, v0
	v_mov_b32_e32 v24, v0
	v_mov_b32_e32 v25, v0
	v_mov_b32_e32 v26, v0
	v_mov_b32_e32 v27, v0
	v_mov_b32_e32 v28, v0
	v_mov_b32_e32 v29, v0
	v_mov_b32_e32 v30, v0
	v_mov_b32_e32 v31, v0
	v_mov_b32_e32 v40, v0
	v_mov_b32_e32 v41, v0
	v_mov_b32_e32 v42, v0
	v_mov_b32_e32 v43, v0
	v_mov_b32_e32 v44, v0
	v_mov_b32_e32 v45, v0
	v_mov_b32_e32 v46, v0
	v_mov_b32_e32 v47, v0
	v_mov_b32_e32 v56, v0
	v_mov_b32_e32 v57, v0
	v_mov_b32_e32 v58, v0
	v_mov_b32_e32 v59, v0
	v_mov_b32_e32 v60, v0
	v_mov_b32_e32 v61, v0
	v_mov_b32_e32 v62, v0
	v_mov_b32_e32 v63, v0
	v_mov_b32_e32 v64, v0
	v_mov_b32_e32 v65, v0
	v_mov_b32_e32 v66, v0
	v_mov_b32_e32 v67, v0
	v_mov_b32_e32 v68, v0
	v_mov_b32_e32 v69, v0
	v_mov_b32_e32 v70, v0
	v_mov_b32_e32 v71, v0
	v_mov_b32_e32 v80, v0
	v_mov_b32_e32 v81, v0
	v_mov_b32_e32 v82, v0
	v_mov_b32_e32 v83, v0
	v_mov_b32_e32 v84, v0
	v_mov_b32_e32 v85, v0
	v_mov_b32_e32 v86, v0
	v_mov_b32_e32 v87, v0
	v_mov_b32_e32 v96, v0
	v_mov_b32_e32 v97, v0
	v_mov_b32_e32 v98, v0
	v_mov_b32_e32 v99, v0
	v_mov_b32_e32 v100, v0
	v_mov_b32_e32 v101, v0
	v_mov_b32_e32 v102, v0
	v_mov_b32_e32 v103, v0
	v_mov_b32_e32 v112, v0
	v_mov_b32_e32 v113, v0
	v_mov_b32_e32 v114, v0
	v_mov_b32_e32 v115, v0
	v_mov_b32_e32 v116, v0
	v_mov_b32_e32 v117, v0
	v_mov_b32_e32 v118, v0
	v_mov_b32_e32 v119, v0
	v_mov_b32_e32 v72, v0
	v_mov_b32_e32 v73, v0
	v_mov_b32_e32 v74, v0
	v_mov_b32_e32 v75, v0
	v_mov_b32_e32 v76, v0
	v_mov_b32_e32 v77, v0
	v_mov_b32_e32 v78, v0
	v_mov_b32_e32 v79, v0
	v_mov_b32_e32 v88, v0
	v_mov_b32_e32 v89, v0
	v_mov_b32_e32 v90, v0
	v_mov_b32_e32 v91, v0
	v_mov_b32_e32 v92, v0
	v_mov_b32_e32 v93, v0
	v_mov_b32_e32 v94, v0
	v_mov_b32_e32 v95, v0
	v_mov_b32_e32 v104, v0
	v_mov_b32_e32 v105, v0
	v_mov_b32_e32 v106, v0
	v_mov_b32_e32 v107, v0
	v_mov_b32_e32 v108, v0
	v_mov_b32_e32 v109, v0
	v_mov_b32_e32 v110, v0
	v_mov_b32_e32 v111, v0
	v_mov_b32_e32 v120, v0
	v_mov_b32_e32 v121, v0
	v_mov_b32_e32 v122, v0
	v_mov_b32_e32 v123, v0
	v_mov_b32_e32 v124, v0
	v_mov_b32_e32 v125, v0
	v_mov_b32_e32 v126, v0
	v_mov_b32_e32 v127, v0
	.p2align 3

.LBB0_803:
	s_ashr_i32 s9, s8, 31
	v_cmp_lt_i64_e32 vcc, s[14:15], v[142:143]
	s_lshl_b64 s[14:15], s[8:9], 20
	v_readlane_b32 s18, v247, 9
	v_readlane_b32 s19, v247, 10
	s_add_u32 s14, s18, s14
	s_addc_u32 s15, s19, s15
	s_and_b64 s[18:19], vcc, exec
	s_cselect_b32 s9, s15, s21
	s_cselect_b32 s17, s14, s20
	s_ashr_i32 s7, s6, 31
	s_lshl_b64 s[18:19], s[6:7], 20
	s_add_u32 s18, s27, s18
	s_addc_u32 s19, s28, s19
	s_and_b64 s[24:25], vcc, exec
	s_cselect_b32 s7, s19, s23
	s_cselect_b32 s42, s18, s22
	s_add_u32 s20, s20, 0x80080
	s_addc_u32 s21, s21, 0
	s_add_u32 s43, s22, 0x100
	v_mov_b32_e32 v0, 0
	s_addc_u32 s44, s23, 0
	s_mov_b32 s45, -2
	v_mov_b32_e32 v1, v0
	v_mov_b32_e32 v2, v0
	v_mov_b32_e32 v3, v0
	v_mov_b32_e32 v4, v0
	v_mov_b32_e32 v5, v0
	v_mov_b32_e32 v6, v0
	v_mov_b32_e32 v7, v0
	v_mov_b32_e32 v8, v0
	v_mov_b32_e32 v9, v0
	v_mov_b32_e32 v10, v0
	v_mov_b32_e32 v11, v0
	v_mov_b32_e32 v12, v0
	v_mov_b32_e32 v13, v0
	v_mov_b32_e32 v14, v0
	v_mov_b32_e32 v15, v0
	v_mov_b32_e32 v24, v0
	v_mov_b32_e32 v25, v0
	v_mov_b32_e32 v26, v0
	v_mov_b32_e32 v27, v0
	v_mov_b32_e32 v28, v0
	v_mov_b32_e32 v29, v0
	v_mov_b32_e32 v30, v0
	v_mov_b32_e32 v31, v0
	v_mov_b32_e32 v40, v0
	v_mov_b32_e32 v41, v0
	v_mov_b32_e32 v42, v0
	v_mov_b32_e32 v43, v0
	v_mov_b32_e32 v44, v0
	v_mov_b32_e32 v45, v0
	v_mov_b32_e32 v46, v0
	v_mov_b32_e32 v47, v0
	v_mov_b32_e32 v16, v0
	v_mov_b32_e32 v17, v0
	v_mov_b32_e32 v18, v0
	v_mov_b32_e32 v19, v0
	v_mov_b32_e32 v20, v0
	v_mov_b32_e32 v21, v0
	v_mov_b32_e32 v22, v0
	v_mov_b32_e32 v23, v0
	v_mov_b32_e32 v32, v0
	v_mov_b32_e32 v33, v0
	v_mov_b32_e32 v34, v0
	v_mov_b32_e32 v35, v0
	v_mov_b32_e32 v36, v0
	v_mov_b32_e32 v37, v0
	v_mov_b32_e32 v38, v0
	v_mov_b32_e32 v39, v0
	v_mov_b32_e32 v48, v0
	v_mov_b32_e32 v49, v0
	v_mov_b32_e32 v50, v0
	v_mov_b32_e32 v51, v0
	v_mov_b32_e32 v52, v0
	v_mov_b32_e32 v53, v0
	v_mov_b32_e32 v54, v0
	v_mov_b32_e32 v55, v0
	v_mov_b32_e32 v56, v0
	v_mov_b32_e32 v57, v0
	v_mov_b32_e32 v58, v0
	v_mov_b32_e32 v59, v0
	v_mov_b32_e32 v60, v0
	v_mov_b32_e32 v61, v0
	v_mov_b32_e32 v62, v0
	v_mov_b32_e32 v63, v0
	v_mov_b32_e32 v64, v0
	v_mov_b32_e32 v65, v0
	v_mov_b32_e32 v66, v0
	v_mov_b32_e32 v67, v0
	v_mov_b32_e32 v68, v0
	v_mov_b32_e32 v69, v0
	v_mov_b32_e32 v70, v0
	v_mov_b32_e32 v71, v0
	v_mov_b32_e32 v72, v0
	v_mov_b32_e32 v73, v0
	v_mov_b32_e32 v74, v0
	v_mov_b32_e32 v75, v0
	v_mov_b32_e32 v76, v0
	v_mov_b32_e32 v77, v0
	v_mov_b32_e32 v78, v0
	v_mov_b32_e32 v79, v0
	v_mov_b32_e32 v88, v0
	v_mov_b32_e32 v89, v0
	v_mov_b32_e32 v90, v0
	v_mov_b32_e32 v91, v0
	v_mov_b32_e32 v92, v0
	v_mov_b32_e32 v93, v0
	v_mov_b32_e32 v94, v0
	v_mov_b32_e32 v95, v0
	v_mov_b32_e32 v104, v0
	v_mov_b32_e32 v105, v0
	v_mov_b32_e32 v106, v0
	v_mov_b32_e32 v107, v0
	v_mov_b32_e32 v108, v0
	v_mov_b32_e32 v109, v0
	v_mov_b32_e32 v110, v0
	v_mov_b32_e32 v111, v0
	v_mov_b32_e32 v80, v0
	v_mov_b32_e32 v81, v0
	v_mov_b32_e32 v82, v0
	v_mov_b32_e32 v83, v0
	v_mov_b32_e32 v84, v0
	v_mov_b32_e32 v85, v0
	v_mov_b32_e32 v86, v0
	v_mov_b32_e32 v87, v0
	v_mov_b32_e32 v96, v0
	v_mov_b32_e32 v97, v0
	v_mov_b32_e32 v98, v0
	v_mov_b32_e32 v99, v0
	v_mov_b32_e32 v100, v0
	v_mov_b32_e32 v101, v0
	v_mov_b32_e32 v102, v0
	v_mov_b32_e32 v103, v0
	v_mov_b32_e32 v112, v0
	v_mov_b32_e32 v113, v0
	v_mov_b32_e32 v114, v0
	v_mov_b32_e32 v115, v0
	v_mov_b32_e32 v116, v0
	v_mov_b32_e32 v117, v0
	v_mov_b32_e32 v118, v0
	v_mov_b32_e32 v119, v0
	v_mov_b32_e32 v120, v0
	v_mov_b32_e32 v121, v0
	v_mov_b32_e32 v122, v0
	v_mov_b32_e32 v123, v0
	v_mov_b32_e32 v124, v0
	v_mov_b32_e32 v125, v0
	v_mov_b32_e32 v126, v0
	v_mov_b32_e32 v127, v0
	.p2align 3

.LBB0_1407:
	s_ashr_i32 s9, s8, 31
	s_lshl_b64 s[12:13], s[8:9], 21
	v_readlane_b32 s14, v247, 9
	v_readlane_b32 s15, v247, 10
	s_add_u32 s12, s14, s12
	s_addc_u32 s13, s15, s13
	s_ashr_i32 s7, s6, 31
	s_lshl_b64 s[14:15], s[6:7], 21
	s_add_u32 s14, s25, s14
	s_addc_u32 s15, s26, s15
	s_cmp_lt_i32 s45, 1
	s_cbranch_scc1 .LBB0_1403
	s_and_b64 s[22:23], s[22:23], exec
	s_cselect_b32 s7, s13, s19
	s_cselect_b32 s9, s12, s18
	s_cselect_b32 s46, s15, s21
	s_cselect_b32 s47, s14, s20
	s_add_i32 s48, s45, -2
	s_add_u32 s18, s18, 0x100080
	s_addc_u32 s19, s19, 0
	s_add_u32 s49, s20, 0x100
	v_mov_b32_e32 v0, 0
	s_addc_u32 s50, s21, 0
	s_mov_b32 s20, 0
	v_mov_b32_e32 v1, v0
	v_mov_b32_e32 v2, v0
	v_mov_b32_e32 v3, v0
	v_mov_b32_e32 v4, v0
	v_mov_b32_e32 v5, v0
	v_mov_b32_e32 v6, v0
	v_mov_b32_e32 v7, v0
	v_mov_b32_e32 v16, v0
	v_mov_b32_e32 v17, v0
	v_mov_b32_e32 v18, v0
	v_mov_b32_e32 v19, v0
	v_mov_b32_e32 v20, v0
	v_mov_b32_e32 v21, v0
	v_mov_b32_e32 v22, v0
	v_mov_b32_e32 v23, v0
	v_mov_b32_e32 v32, v0
	v_mov_b32_e32 v33, v0
	v_mov_b32_e32 v34, v0
	v_mov_b32_e32 v35, v0
	v_mov_b32_e32 v36, v0
	v_mov_b32_e32 v37, v0
	v_mov_b32_e32 v38, v0
	v_mov_b32_e32 v39, v0
	v_mov_b32_e32 v48, v0
	v_mov_b32_e32 v49, v0
	v_mov_b32_e32 v50, v0
	v_mov_b32_e32 v51, v0
	v_mov_b32_e32 v52, v0
	v_mov_b32_e32 v53, v0
	v_mov_b32_e32 v54, v0
	v_mov_b32_e32 v55, v0
	v_mov_b32_e32 v8, v0
	v_mov_b32_e32 v9, v0
	v_mov_b32_e32 v10, v0
	v_mov_b32_e32 v11, v0
	v_mov_b32_e32 v12, v0
	v_mov_b32_e32 v13, v0
	v_mov_b32_e32 v14, v0
	v_mov_b32_e32 v15, v0
	v_mov_b32_e32 v24, v0
	v_mov_b32_e32 v25, v0
	v_mov_b32_e32 v26, v0
	v_mov_b32_e32 v27, v0
	v_mov_b32_e32 v28, v0
	v_mov_b32_e32 v29, v0
	v_mov_b32_e32 v30, v0
	v_mov_b32_e32 v31, v0
	v_mov_b32_e32 v40, v0
	v_mov_b32_e32 v41, v0
	v_mov_b32_e32 v42, v0
	v_mov_b32_e32 v43, v0
	v_mov_b32_e32 v44, v0
	v_mov_b32_e32 v45, v0
	v_mov_b32_e32 v46, v0
	v_mov_b32_e32 v47, v0
	v_mov_b32_e32 v56, v0
	v_mov_b32_e32 v57, v0
	v_mov_b32_e32 v58, v0
	v_mov_b32_e32 v59, v0
	v_mov_b32_e32 v60, v0
	v_mov_b32_e32 v61, v0
	v_mov_b32_e32 v62, v0
	v_mov_b32_e32 v63, v0
	v_mov_b32_e32 v64, v0
	v_mov_b32_e32 v65, v0
	v_mov_b32_e32 v66, v0
	v_mov_b32_e32 v67, v0
	v_mov_b32_e32 v68, v0
	v_mov_b32_e32 v69, v0
	v_mov_b32_e32 v70, v0
	v_mov_b32_e32 v71, v0
	v_mov_b32_e32 v80, v0
	v_mov_b32_e32 v81, v0
	v_mov_b32_e32 v82, v0
	v_mov_b32_e32 v83, v0
	v_mov_b32_e32 v84, v0
	v_mov_b32_e32 v85, v0
	v_mov_b32_e32 v86, v0
	v_mov_b32_e32 v87, v0
	v_mov_b32_e32 v96, v0
	v_mov_b32_e32 v97, v0
	v_mov_b32_e32 v98, v0
	v_mov_b32_e32 v99, v0
	v_mov_b32_e32 v100, v0
	v_mov_b32_e32 v101, v0
	v_mov_b32_e32 v102, v0
	v_mov_b32_e32 v103, v0
	v_mov_b32_e32 v112, v0
	v_mov_b32_e32 v113, v0
	v_mov_b32_e32 v114, v0
	v_mov_b32_e32 v115, v0
	v_mov_b32_e32 v116, v0
	v_mov_b32_e32 v117, v0
	v_mov_b32_e32 v118, v0
	v_mov_b32_e32 v119, v0
	v_mov_b32_e32 v72, v0
	v_mov_b32_e32 v73, v0
	v_mov_b32_e32 v74, v0
	v_mov_b32_e32 v75, v0
	v_mov_b32_e32 v76, v0
	v_mov_b32_e32 v77, v0
	v_mov_b32_e32 v78, v0
	v_mov_b32_e32 v79, v0
	v_mov_b32_e32 v88, v0
	v_mov_b32_e32 v89, v0
	v_mov_b32_e32 v90, v0
	v_mov_b32_e32 v91, v0
	v_mov_b32_e32 v92, v0
	v_mov_b32_e32 v93, v0
	v_mov_b32_e32 v94, v0
	v_mov_b32_e32 v95, v0
	v_mov_b32_e32 v104, v0
	v_mov_b32_e32 v105, v0
	v_mov_b32_e32 v106, v0
	v_mov_b32_e32 v107, v0
	v_mov_b32_e32 v108, v0
	v_mov_b32_e32 v109, v0
	v_mov_b32_e32 v110, v0
	v_mov_b32_e32 v111, v0
	v_mov_b32_e32 v120, v0
	v_mov_b32_e32 v121, v0
	v_mov_b32_e32 v122, v0
	v_mov_b32_e32 v123, v0
	v_mov_b32_e32 v124, v0
	v_mov_b32_e32 v125, v0
	v_mov_b32_e32 v126, v0
	v_mov_b32_e32 v127, v0
	.p2align 3

.LBB0_1563:
	s_ashr_i32 s15, s14, 31
	v_cmp_lt_i64_e32 vcc, s[16:17], v[140:141]
	s_lshl_b64 s[16:17], s[14:15], 20
	v_readlane_b32 s18, v247, 9
	v_readlane_b32 s19, v247, 10
	s_add_u32 s16, s18, s16
	s_addc_u32 s17, s19, s17
	s_and_b64 s[18:19], vcc, exec
	s_cselect_b32 s15, s17, s23
	s_cselect_b32 s48, s16, s22
	s_ashr_i32 s13, s12, 31
	s_lshl_b64 s[18:19], s[12:13], 20
	s_add_u32 s18, s29, s18
	s_addc_u32 s19, s30, s19
	s_and_b64 s[26:27], vcc, exec
	s_cselect_b32 s13, s19, s25
	s_cselect_b32 s49, s18, s24
	s_add_u32 s22, s22, 0x80080
	s_addc_u32 s23, s23, 0
	s_add_u32 s50, s24, 0x100
	v_mov_b32_e32 v0, 0
	s_addc_u32 s51, s25, 0
	s_mov_b32 s52, -2
	v_mov_b32_e32 v1, v0
	v_mov_b32_e32 v2, v0
	v_mov_b32_e32 v3, v0
	v_mov_b32_e32 v4, v0
	v_mov_b32_e32 v5, v0
	v_mov_b32_e32 v6, v0
	v_mov_b32_e32 v7, v0
	v_mov_b32_e32 v16, v0
	v_mov_b32_e32 v17, v0
	v_mov_b32_e32 v18, v0
	v_mov_b32_e32 v19, v0
	v_mov_b32_e32 v20, v0
	v_mov_b32_e32 v21, v0
	v_mov_b32_e32 v22, v0
	v_mov_b32_e32 v23, v0
	v_mov_b32_e32 v32, v0
	v_mov_b32_e32 v33, v0
	v_mov_b32_e32 v34, v0
	v_mov_b32_e32 v35, v0
	v_mov_b32_e32 v36, v0
	v_mov_b32_e32 v37, v0
	v_mov_b32_e32 v38, v0
	v_mov_b32_e32 v39, v0
	v_mov_b32_e32 v48, v0
	v_mov_b32_e32 v49, v0
	v_mov_b32_e32 v50, v0
	v_mov_b32_e32 v51, v0
	v_mov_b32_e32 v52, v0
	v_mov_b32_e32 v53, v0
	v_mov_b32_e32 v54, v0
	v_mov_b32_e32 v55, v0
	v_mov_b32_e32 v8, v0
	v_mov_b32_e32 v9, v0
	v_mov_b32_e32 v10, v0
	v_mov_b32_e32 v11, v0
	v_mov_b32_e32 v12, v0
	v_mov_b32_e32 v13, v0
	v_mov_b32_e32 v14, v0
	v_mov_b32_e32 v15, v0
	v_mov_b32_e32 v24, v0
	v_mov_b32_e32 v25, v0
	v_mov_b32_e32 v26, v0
	v_mov_b32_e32 v27, v0
	v_mov_b32_e32 v28, v0
	v_mov_b32_e32 v29, v0
	v_mov_b32_e32 v30, v0
	v_mov_b32_e32 v31, v0
	v_mov_b32_e32 v40, v0
	v_mov_b32_e32 v41, v0
	v_mov_b32_e32 v42, v0
	v_mov_b32_e32 v43, v0
	v_mov_b32_e32 v44, v0
	v_mov_b32_e32 v45, v0
	v_mov_b32_e32 v46, v0
	v_mov_b32_e32 v47, v0
	v_mov_b32_e32 v56, v0
	v_mov_b32_e32 v57, v0
	v_mov_b32_e32 v58, v0
	v_mov_b32_e32 v59, v0
	v_mov_b32_e32 v60, v0
	v_mov_b32_e32 v61, v0
	v_mov_b32_e32 v62, v0
	v_mov_b32_e32 v63, v0
	v_mov_b32_e32 v64, v0
	v_mov_b32_e32 v65, v0
	v_mov_b32_e32 v66, v0
	v_mov_b32_e32 v67, v0
	v_mov_b32_e32 v68, v0
	v_mov_b32_e32 v69, v0
	v_mov_b32_e32 v70, v0
	v_mov_b32_e32 v71, v0
	v_mov_b32_e32 v80, v0
	v_mov_b32_e32 v81, v0
	v_mov_b32_e32 v82, v0
	v_mov_b32_e32 v83, v0
	v_mov_b32_e32 v84, v0
	v_mov_b32_e32 v85, v0
	v_mov_b32_e32 v86, v0
	v_mov_b32_e32 v87, v0
	v_mov_b32_e32 v96, v0
	v_mov_b32_e32 v97, v0
	v_mov_b32_e32 v98, v0
	v_mov_b32_e32 v99, v0
	v_mov_b32_e32 v100, v0
	v_mov_b32_e32 v101, v0
	v_mov_b32_e32 v102, v0
	v_mov_b32_e32 v103, v0
	v_mov_b32_e32 v112, v0
	v_mov_b32_e32 v113, v0
	v_mov_b32_e32 v114, v0
	v_mov_b32_e32 v115, v0
	v_mov_b32_e32 v116, v0
	v_mov_b32_e32 v117, v0
	v_mov_b32_e32 v118, v0
	v_mov_b32_e32 v119, v0
	v_mov_b32_e32 v72, v0
	v_mov_b32_e32 v73, v0
	v_mov_b32_e32 v74, v0
	v_mov_b32_e32 v75, v0
	v_mov_b32_e32 v76, v0
	v_mov_b32_e32 v77, v0
	v_mov_b32_e32 v78, v0
	v_mov_b32_e32 v79, v0
	v_mov_b32_e32 v88, v0
	v_mov_b32_e32 v89, v0
	v_mov_b32_e32 v90, v0
	v_mov_b32_e32 v91, v0
	v_mov_b32_e32 v92, v0
	v_mov_b32_e32 v93, v0
	v_mov_b32_e32 v94, v0
	v_mov_b32_e32 v95, v0
	v_mov_b32_e32 v104, v0
	v_mov_b32_e32 v105, v0
	v_mov_b32_e32 v106, v0
	v_mov_b32_e32 v107, v0
	v_mov_b32_e32 v108, v0
	v_mov_b32_e32 v109, v0
	v_mov_b32_e32 v110, v0
	v_mov_b32_e32 v111, v0
	v_mov_b32_e32 v120, v0
	v_mov_b32_e32 v121, v0
	v_mov_b32_e32 v122, v0
	v_mov_b32_e32 v123, v0
	v_mov_b32_e32 v124, v0
	v_mov_b32_e32 v125, v0
	v_mov_b32_e32 v126, v0
	v_mov_b32_e32 v127, v0
	.p2align 3

.LBB0_1629:
	s_ashr_i32 s13, s12, 31
	s_lshl_b64 s[16:17], s[12:13], 22
	v_readlane_b32 s18, v248, 63
	v_readlane_b32 s19, v247, 0
	s_add_u32 s16, s18, s16
	s_addc_u32 s17, s19, s17
	s_ashr_i32 s11, s10, 31
	s_lshl_b64 s[18:19], s[10:11], 22
	s_add_u32 s18, s27, s18
	s_addc_u32 s19, s28, s19
	s_cmp_lt_i32 s33, 1
	s_cbranch_scc1 .LBB0_1625
	s_and_b64 s[24:25], s[24:25], exec
	s_cselect_b32 s11, s17, s21
	s_cselect_b32 s13, s16, s20
	s_cselect_b32 s46, s19, s23
	s_cselect_b32 s47, s18, s22
	s_add_i32 s48, s33, -2
	s_add_u32 s20, s20, 0x200080
	s_addc_u32 s21, s21, 0
	s_add_u32 s49, s22, 0x100
	v_mov_b32_e32 v0, 0
	s_addc_u32 s50, s23, 0
	s_mov_b32 s22, 0
	v_mov_b32_e32 v1, v0
	v_mov_b32_e32 v2, v0
	v_mov_b32_e32 v3, v0
	v_mov_b32_e32 v4, v0
	v_mov_b32_e32 v5, v0
	v_mov_b32_e32 v6, v0
	v_mov_b32_e32 v7, v0
	v_mov_b32_e32 v16, v0
	v_mov_b32_e32 v17, v0
	v_mov_b32_e32 v18, v0
	v_mov_b32_e32 v19, v0
	v_mov_b32_e32 v20, v0
	v_mov_b32_e32 v21, v0
	v_mov_b32_e32 v22, v0
	v_mov_b32_e32 v23, v0
	v_mov_b32_e32 v32, v0
	v_mov_b32_e32 v33, v0
	v_mov_b32_e32 v34, v0
	v_mov_b32_e32 v35, v0
	v_mov_b32_e32 v36, v0
	v_mov_b32_e32 v37, v0
	v_mov_b32_e32 v38, v0
	v_mov_b32_e32 v39, v0
	v_mov_b32_e32 v48, v0
	v_mov_b32_e32 v49, v0
	v_mov_b32_e32 v50, v0
	v_mov_b32_e32 v51, v0
	v_mov_b32_e32 v52, v0
	v_mov_b32_e32 v53, v0
	v_mov_b32_e32 v54, v0
	v_mov_b32_e32 v55, v0
	v_mov_b32_e32 v8, v0
	v_mov_b32_e32 v9, v0
	v_mov_b32_e32 v10, v0
	v_mov_b32_e32 v11, v0
	v_mov_b32_e32 v12, v0
	v_mov_b32_e32 v13, v0
	v_mov_b32_e32 v14, v0
	v_mov_b32_e32 v15, v0
	v_mov_b32_e32 v24, v0
	v_mov_b32_e32 v25, v0
	v_mov_b32_e32 v26, v0
	v_mov_b32_e32 v27, v0
	v_mov_b32_e32 v28, v0
	v_mov_b32_e32 v29, v0
	v_mov_b32_e32 v30, v0
	v_mov_b32_e32 v31, v0
	v_mov_b32_e32 v40, v0
	v_mov_b32_e32 v41, v0
	v_mov_b32_e32 v42, v0
	v_mov_b32_e32 v43, v0
	v_mov_b32_e32 v44, v0
	v_mov_b32_e32 v45, v0
	v_mov_b32_e32 v46, v0
	v_mov_b32_e32 v47, v0
	v_mov_b32_e32 v56, v0
	v_mov_b32_e32 v57, v0
	v_mov_b32_e32 v58, v0
	v_mov_b32_e32 v59, v0
	v_mov_b32_e32 v60, v0
	v_mov_b32_e32 v61, v0
	v_mov_b32_e32 v62, v0
	v_mov_b32_e32 v63, v0
	v_mov_b32_e32 v64, v0
	v_mov_b32_e32 v65, v0
	v_mov_b32_e32 v66, v0
	v_mov_b32_e32 v67, v0
	v_mov_b32_e32 v68, v0
	v_mov_b32_e32 v69, v0
	v_mov_b32_e32 v70, v0
	v_mov_b32_e32 v71, v0
	v_mov_b32_e32 v80, v0
	v_mov_b32_e32 v81, v0
	v_mov_b32_e32 v82, v0
	v_mov_b32_e32 v83, v0
	v_mov_b32_e32 v84, v0
	v_mov_b32_e32 v85, v0
	v_mov_b32_e32 v86, v0
	v_mov_b32_e32 v87, v0
	v_mov_b32_e32 v96, v0
	v_mov_b32_e32 v97, v0
	v_mov_b32_e32 v98, v0
	v_mov_b32_e32 v99, v0
	v_mov_b32_e32 v100, v0
	v_mov_b32_e32 v101, v0
	v_mov_b32_e32 v102, v0
	v_mov_b32_e32 v103, v0
	v_mov_b32_e32 v112, v0
	v_mov_b32_e32 v113, v0
	v_mov_b32_e32 v114, v0
	v_mov_b32_e32 v115, v0
	v_mov_b32_e32 v116, v0
	v_mov_b32_e32 v117, v0
	v_mov_b32_e32 v118, v0
	v_mov_b32_e32 v119, v0
	v_mov_b32_e32 v72, v0
	v_mov_b32_e32 v73, v0
	v_mov_b32_e32 v74, v0
	v_mov_b32_e32 v75, v0
	v_mov_b32_e32 v76, v0
	v_mov_b32_e32 v77, v0
	v_mov_b32_e32 v78, v0
	v_mov_b32_e32 v79, v0
	v_mov_b32_e32 v88, v0
	v_mov_b32_e32 v89, v0
	v_mov_b32_e32 v90, v0
	v_mov_b32_e32 v91, v0
	v_mov_b32_e32 v92, v0
	v_mov_b32_e32 v93, v0
	v_mov_b32_e32 v94, v0
	v_mov_b32_e32 v95, v0
	v_mov_b32_e32 v104, v0
	v_mov_b32_e32 v105, v0
	v_mov_b32_e32 v106, v0
	v_mov_b32_e32 v107, v0
	v_mov_b32_e32 v108, v0
	v_mov_b32_e32 v109, v0
	v_mov_b32_e32 v110, v0
	v_mov_b32_e32 v111, v0
	v_mov_b32_e32 v120, v0
	v_mov_b32_e32 v121, v0
	v_mov_b32_e32 v122, v0
	v_mov_b32_e32 v123, v0
	v_mov_b32_e32 v124, v0
	v_mov_b32_e32 v125, v0
	v_mov_b32_e32 v126, v0
	v_mov_b32_e32 v127, v0
	s_mov_b32 s62, s52
	.p2align 3
